# cross-attention epilogue: v_permlane32_swap pairs + dwordx4 stores (strategy 7.3)
# speedup vs baseline: 1.0102x; 1.0003x over previous
; #define LAS __attribute__((address_space(3)))
; __device__ __forceinline__ unsigned cvtpk(float lo, float hi) { f32x2_t v = {lo, hi}; bf16x2_t b = __builtin_convertvector(v, bf16x2_t); return __builtin_bit_cast(unsigned, b); }
; template <bool DIFF> ...
;     ...
;     l_run += __shfl_xor(l_run, 32);
;     ...
;     const float inv = 1.f / l_run;
;     if (DIFF) {
;         __syncthreads();
;         LAS float* ex = (LAS float*)lds + (wid & 3) * 4096;
;         if (c == 1) { const float f = inv * lam;
; #pragma unroll
;             for (int i = 0; i < 4; ++i)
; #pragma unroll
;                 for (int r = 0; r < 16; ++r) ex[(i * 16 + r) * 64 + lane] = o[i][r] * f; }
;         __syncthreads();
;         if (c == 0) {
;             float ss = 0.f;
; #pragma unroll
;             for (int i = 0; i < 4; ++i)
; #pragma unroll
;                 for (int r = 0; r < 16; ++r) { const float v = o[i][r] * inv - ex[(i * 16 + r) * 64 + lane]; o[i][r] = v; ss += v * v; }
;             ss += __shfl_xor(ss, 32);
;             const float rstd = rsqrtf(ss * (1.f / 128.f) + 1e-6f) * oscale;
;             bf16_t* orow = Op + (size_t)(qr + l32) * opitch;
; #pragma unroll
;             for (int i = 0; i < 4; ++i)
; #pragma unroll
;                 for (int r4 = 0; r4 < 4; ++r4) { const int dv = i * 32 + r4 * 8 + hi * 4; const f32x4 gg = *(const f32x4*)(subg + dv); u32x2 w;
;                     w.x = cvtpk(o[i][4 * r4] * rstd * gg[0], o[i][4 * r4 + 1] * rstd * gg[1]); w.y = cvtpk(o[i][4 * r4 + 2] * rstd * gg[2], o[i][4 * r4 + 3] * rstd * gg[3]);
;                     *(u32x2*)(orow + dv) = w; }
;         }
;     } else {
;         bf16_t* orow = Op + (size_t)(qr + l32) * opitch + c * 128;
; #pragma unroll
;         for (int i = 0; i < 4; ++i)
; #pragma unroll
;             for (int r4 = 0; r4 < 4; ++r4) { const int dv = i * 32 + r4 * 8 + hi * 4; u32x2 w;
;                 w.x = cvtpk(o[i][4 * r4] * inv, o[i][4 * r4 + 1] * inv); w.y = cvtpk(o[i][4 * r4 + 2] * inv, o[i][4 * r4 + 3] * inv);
;                 *(u32x2*)(orow + dv) = w; }
.LBB0_250:
	ds_bpermute_b32 v0, v202, v203
	v_readlane_b32 s18, v252, 26
	v_readlane_b32 s19, v252, 27
	s_add_u32 s16, s18, s16
	s_addc_u32 s17, s19, s17
	s_waitcnt lgkmcnt(0)
	v_add_f32_e32 v0, v203, v0
	v_div_scale_f32 v66, s[18:19], v0, v0, 1.0
	v_rcp_f32_e32 v67, v66
	s_ashr_i32 s14, s14, 1
	s_and_b32 s14, s14, 0xffffff80
	s_ashr_i32 s15, s14, 31
	v_fma_f32 v68, -v66, v67, 1.0
	v_fmac_f32_e32 v67, v68, v67
	v_div_scale_f32 v68, vcc, 1.0, v0, 1.0
	v_mul_f32_e32 v69, v68, v67
	v_fma_f32 v70, -v66, v69, v68
	v_fmac_f32_e32 v69, v70, v67
	v_fma_f32 v66, -v66, v69, v68
	v_div_fmas_f32 v66, v66, v67, v69
	v_div_fixup_f32 v66, v66, v0, 1.0
	v_lshlrev_b32_e32 v0, 11, v199
	v_lshl_add_u64 v[68:69], s[16:17], 0, v[0:1]
	v_lshl_add_u64 v[68:69], s[14:15], 1, v[68:69]
	v_lshlrev_b32_e32 v0, 2, v197
	v_lshl_add_u64 v[70:71], v[68:69], 0, v[0:1]
	v_pk_mul_f32 v[50:51], v[50:51], v[66:67] op_sel_hi:[1,0]
	v_pk_mul_f32 v[52:53], v[52:53], v[66:67] op_sel_hi:[1,0]
	v_pk_mul_f32 v[54:55], v[54:55], v[66:67] op_sel_hi:[1,0]
	v_pk_mul_f32 v[56:57], v[56:57], v[66:67] op_sel_hi:[1,0]
	v_pk_mul_f32 v[58:59], v[58:59], v[66:67] op_sel_hi:[1,0]
	v_pk_mul_f32 v[60:61], v[60:61], v[66:67] op_sel_hi:[1,0]
	v_pk_mul_f32 v[62:63], v[62:63], v[66:67] op_sel_hi:[1,0]
	v_pk_mul_f32 v[64:65], v[64:65], v[66:67] op_sel_hi:[1,0]
	v_pk_mul_f32 v[34:35], v[34:35], v[66:67] op_sel_hi:[1,0]
	v_pk_mul_f32 v[36:37], v[36:37], v[66:67] op_sel_hi:[1,0]
	v_pk_mul_f32 v[38:39], v[38:39], v[66:67] op_sel_hi:[1,0]
	v_pk_mul_f32 v[40:41], v[40:41], v[66:67] op_sel_hi:[1,0]
	v_pk_mul_f32 v[42:43], v[42:43], v[66:67] op_sel_hi:[1,0]
	v_pk_mul_f32 v[44:45], v[44:45], v[66:67] op_sel_hi:[1,0]
	v_pk_mul_f32 v[46:47], v[46:47], v[66:67] op_sel_hi:[1,0]
	v_pk_mul_f32 v[48:49], v[48:49], v[66:67] op_sel_hi:[1,0]
	v_pk_mul_f32 v[18:19], v[18:19], v[66:67] op_sel_hi:[1,0]
	v_pk_mul_f32 v[20:21], v[20:21], v[66:67] op_sel_hi:[1,0]
	v_pk_mul_f32 v[22:23], v[22:23], v[66:67] op_sel_hi:[1,0]
	v_pk_mul_f32 v[24:25], v[24:25], v[66:67] op_sel_hi:[1,0]
	v_pk_mul_f32 v[26:27], v[26:27], v[66:67] op_sel_hi:[1,0]
	v_pk_mul_f32 v[28:29], v[28:29], v[66:67] op_sel_hi:[1,0]
	v_pk_mul_f32 v[30:31], v[30:31], v[66:67] op_sel_hi:[1,0]
	v_pk_mul_f32 v[32:33], v[32:33], v[66:67] op_sel_hi:[1,0]
	v_pk_mul_f32 v[2:3], v[2:3], v[66:67] op_sel_hi:[1,0]
	v_pk_mul_f32 v[4:5], v[4:5], v[66:67] op_sel_hi:[1,0]
	v_pk_mul_f32 v[6:7], v[6:7], v[66:67] op_sel_hi:[1,0]
	v_pk_mul_f32 v[8:9], v[8:9], v[66:67] op_sel_hi:[1,0]
	v_pk_mul_f32 v[10:11], v[10:11], v[66:67] op_sel_hi:[1,0]
	v_pk_mul_f32 v[12:13], v[12:13], v[66:67] op_sel_hi:[1,0]
	v_pk_mul_f32 v[14:15], v[14:15], v[66:67] op_sel_hi:[1,0]
	v_pk_mul_f32 v[16:17], v[16:17], v[66:67] op_sel_hi:[1,0]
	v_cvt_pk_bf16_f32 v50, v50, v51
	v_cvt_pk_bf16_f32 v51, v52, v53
	v_cvt_pk_bf16_f32 v52, v54, v55
	v_cvt_pk_bf16_f32 v53, v56, v57
	v_cvt_pk_bf16_f32 v58, v58, v59
	v_cvt_pk_bf16_f32 v59, v60, v61
	v_cvt_pk_bf16_f32 v60, v62, v63
	v_cvt_pk_bf16_f32 v61, v64, v65
	v_cvt_pk_bf16_f32 v34, v34, v35
	v_cvt_pk_bf16_f32 v35, v36, v37
	v_cvt_pk_bf16_f32 v36, v38, v39
	v_cvt_pk_bf16_f32 v37, v40, v41
	v_cvt_pk_bf16_f32 v42, v42, v43
	v_cvt_pk_bf16_f32 v43, v44, v45
	v_cvt_pk_bf16_f32 v44, v46, v47
	v_cvt_pk_bf16_f32 v45, v48, v49
	v_cvt_pk_bf16_f32 v18, v18, v19
	v_cvt_pk_bf16_f32 v19, v20, v21
	v_cvt_pk_bf16_f32 v20, v22, v23
	v_cvt_pk_bf16_f32 v21, v24, v25
	v_cvt_pk_bf16_f32 v26, v26, v27
	v_cvt_pk_bf16_f32 v27, v28, v29
	v_cvt_pk_bf16_f32 v28, v30, v31
	v_cvt_pk_bf16_f32 v29, v32, v33
	v_cvt_pk_bf16_f32 v2, v2, v3
	v_cvt_pk_bf16_f32 v3, v4, v5
	v_cvt_pk_bf16_f32 v4, v6, v7
	v_cvt_pk_bf16_f32 v5, v8, v9
	v_cvt_pk_bf16_f32 v10, v10, v11
	v_cvt_pk_bf16_f32 v11, v12, v13
	v_cvt_pk_bf16_f32 v12, v14, v15
	v_cvt_pk_bf16_f32 v13, v16, v17
	s_nop 1
	v_permlane32_swap_b32_e32 v50, v52
	v_permlane32_swap_b32_e32 v51, v53
	v_permlane32_swap_b32_e32 v58, v60
	v_permlane32_swap_b32_e32 v59, v61
	v_permlane32_swap_b32_e32 v34, v36
	v_permlane32_swap_b32_e32 v35, v37
	v_permlane32_swap_b32_e32 v42, v44
	v_permlane32_swap_b32_e32 v43, v45
	v_permlane32_swap_b32_e32 v18, v20
	v_permlane32_swap_b32_e32 v19, v21
	v_permlane32_swap_b32_e32 v26, v28
	v_permlane32_swap_b32_e32 v27, v29
	v_permlane32_swap_b32_e32 v2, v4
	v_permlane32_swap_b32_e32 v3, v5
	v_permlane32_swap_b32_e32 v10, v12
	v_permlane32_swap_b32_e32 v11, v13
	s_movk_i32 s14, 0x80
	s_mov_b64 s[16:17], 0
	s_and_b64 vcc, exec, s[10:11]
	global_store_dwordx4 v[70:71], v[50:53], off
	global_store_dwordx4 v[70:71], v[58:61], off offset:32
	global_store_dwordx4 v[70:71], v[34:37], off offset:64
	global_store_dwordx4 v[70:71], v[42:45], off offset:96
	global_store_dwordx4 v[70:71], v[18:21], off offset:128
	global_store_dwordx4 v[70:71], v[26:29], off offset:160
	global_store_dwordx4 v[70:71], v[2:5], off offset:192
	global_store_dwordx4 v[70:71], v[10:13], off offset:224
	s_cbranch_vccnz .LBB0_240
